# k16 plus: accumulator zeroing before each unit with 64 v_mov_b64 instead of 128 v_mov_b32 (7 of the GEMM phases)
# speedup vs baseline: 1.0188x; 1.0052x over previous
;     __device__ bool next(int i, Unit& u) const { const bool r = base.next(i >> 1, u); u.kh = i & 1; return r; }
; template <class Epi, class Sched, bool ALIGN_EPI = false, bool SP2 = false, bool ABLK = false, bool F8 = false>
; __device__ __forceinline__ void gemm_phase(PG8_LAS unsigned char* lds, const Gemm g, const Sched& S, const Epi& E, const int wave_s) {
;     ...
;         const bool has_next = S.next(ui + 1, nxt); nxt.par = (ui + 1) & 1;
;         const char* nA = has_next ? (const char*)g.A + (size_t)nxt.pm * tstep + nxt.kh * khbA : cA; const char* nB = has_next ? (const char*)g.Bt + (size_t)nxt.pn * tstep + nxt.kh * khb : cB;
;     ...
;         if (!(Epi::MID && cur.kh == 0))
; #pragma unroll
;         for (int a = 0; a < 2; ++a)
; #pragma unroll
;             for (int b = 0; b < 2; ++b)
; #pragma unroll
;                 for (int m = 0; m < 4; ++m)
; #pragma unroll
;                     for (int n = 0; n < 2; ++n) acc[a][b][m][n] = (f32x4){0.f, 0.f, 0.f, 0.f};
;         cur = nxt; cA = nA; cB = nB; ++ui;
.LBB0_222:
	s_ashr_i32 s49, s48, 31
	s_and_b32 s67, s66, 1
	s_lshl_b64 s[50:51], s[48:49], 20
	s_add_u32 s50, s28, s50
	s_addc_u32 s51, s29, s51
	s_and_b64 s[52:53], exec, s[8:9]
	s_cselect_b32 s49, s59, s51
	s_cselect_b32 s77, s58, s50
	s_ashr_i32 s17, s16, 31
	s_lshl_b64 s[52:53], s[16:17], 20
	s_add_u32 s52, s18, s52
	s_addc_u32 s53, s21, s53
	s_and_b64 s[62:63], exec, s[8:9]
	s_cselect_b32 s17, s61, s53
	s_cselect_b32 s78, s60, s52
	s_lshl_b32 s62, s48, 8
	s_ashr_i32 s63, s62, 31
	s_lshl_b32 s72, s67, 10
	s_or_b64 s[8:9], s[44:45], s[8:9]
	s_add_u32 s58, s58, 0x80080
	s_addc_u32 s59, s59, 0
	s_add_u32 s79, s60, 0x100
	v_mov_b64_e32 v[0:1], 0
	s_addc_u32 s80, s61, 0
	s_mov_b32 s81, -2
	s_add_i32 s82, s95, s72
	v_mov_b64_e32 v[2:3], 0
	v_mov_b64_e32 v[8:9], 0
	v_mov_b64_e32 v[10:11], 0
	v_mov_b64_e32 v[16:17], 0
	v_mov_b64_e32 v[18:19], 0
	v_mov_b64_e32 v[24:25], 0
	v_mov_b64_e32 v[26:27], 0
	v_mov_b64_e32 v[32:33], 0
	v_mov_b64_e32 v[34:35], 0
	v_mov_b64_e32 v[40:41], 0
	v_mov_b64_e32 v[42:43], 0
	v_mov_b64_e32 v[48:49], 0
	v_mov_b64_e32 v[50:51], 0
	v_mov_b64_e32 v[56:57], 0
	v_mov_b64_e32 v[58:59], 0
	v_mov_b64_e32 v[4:5], 0
	v_mov_b64_e32 v[6:7], 0
	v_mov_b64_e32 v[12:13], 0
	v_mov_b64_e32 v[14:15], 0
	v_mov_b64_e32 v[20:21], 0
	v_mov_b64_e32 v[22:23], 0
	v_mov_b64_e32 v[28:29], 0
	v_mov_b64_e32 v[30:31], 0
	v_mov_b64_e32 v[36:37], 0
	v_mov_b64_e32 v[38:39], 0
	v_mov_b64_e32 v[44:45], 0
	v_mov_b64_e32 v[46:47], 0
	v_mov_b64_e32 v[52:53], 0
	v_mov_b64_e32 v[54:55], 0
	v_mov_b64_e32 v[60:61], 0
	v_mov_b64_e32 v[62:63], 0
	v_mov_b64_e32 v[64:65], 0
	v_mov_b64_e32 v[66:67], 0
	v_mov_b64_e32 v[72:73], 0
	v_mov_b64_e32 v[74:75], 0
	v_mov_b64_e32 v[80:81], 0
	v_mov_b64_e32 v[82:83], 0
	v_mov_b64_e32 v[88:89], 0
	v_mov_b64_e32 v[90:91], 0
	v_mov_b64_e32 v[96:97], 0
	v_mov_b64_e32 v[98:99], 0
	v_mov_b64_e32 v[104:105], 0
	v_mov_b64_e32 v[106:107], 0
	v_mov_b64_e32 v[112:113], 0
	v_mov_b64_e32 v[114:115], 0
	v_mov_b64_e32 v[120:121], 0
	v_mov_b64_e32 v[122:123], 0
	v_mov_b64_e32 v[68:69], 0
	v_mov_b64_e32 v[70:71], 0
	v_mov_b64_e32 v[76:77], 0
	v_mov_b64_e32 v[78:79], 0
	v_mov_b64_e32 v[84:85], 0
	v_mov_b64_e32 v[86:87], 0
	v_mov_b64_e32 v[92:93], 0
	v_mov_b64_e32 v[94:95], 0
	v_mov_b64_e32 v[100:101], 0
	v_mov_b64_e32 v[102:103], 0
	v_mov_b64_e32 v[108:109], 0
	v_mov_b64_e32 v[110:111], 0
	v_mov_b64_e32 v[116:117], 0
	v_mov_b64_e32 v[118:119], 0
	v_mov_b64_e32 v[124:125], 0
	v_mov_b64_e32 v[126:127], 0
	v_lshl_add_u64 v[154:155], s[62:63], 2, v[146:147]
	s_branch .LBB0_224

; template <class Epi, class Sched, bool ALIGN_EPI = false, bool SP2 = false, bool ABLK = false, bool F8 = false>
; __device__ __forceinline__ void gemm_phase(PG8_LAS unsigned char* lds, const Gemm g, const Sched& S, const Epi& E, const int wave_s) {
;     ...
;         if (!(Epi::MID && cur.kh == 0))
; #pragma unroll
;         for (int a = 0; a < 2; ++a)
; #pragma unroll
;             for (int b = 0; b < 2; ++b)
; #pragma unroll
;                 for (int m = 0; m < 4; ++m)
; #pragma unroll
;                     for (int n = 0; n < 2; ++n) acc[a][b][m][n] = (f32x4){0.f, 0.f, 0.f, 0.f};
;         cur = nxt; cA = nA; cB = nB; ++ui;
.LBB0_303:
	s_add_u32 s67, s50, 0x100
	s_addc_u32 s76, s51, 0
	s_add_u32 s50, s52, 0xc000
	v_mov_b64_e32 v[0:1], 0
	s_addc_u32 s51, s53, 0
	s_mov_b32 s77, -2
	s_waitcnt lgkmcnt(0)
	v_mov_b64_e32 v[2:3], 0
	v_mov_b64_e32 v[4:5], 0
	v_mov_b64_e32 v[6:7], 0
	v_mov_b64_e32 v[16:17], 0
	v_mov_b64_e32 v[18:19], 0
	v_mov_b64_e32 v[20:21], 0
	v_mov_b64_e32 v[22:23], 0
	v_mov_b64_e32 v[32:33], 0
	v_mov_b64_e32 v[34:35], 0
	v_mov_b64_e32 v[36:37], 0
	v_mov_b64_e32 v[38:39], 0
	v_mov_b64_e32 v[48:49], 0
	v_mov_b64_e32 v[50:51], 0
	v_mov_b64_e32 v[52:53], 0
	v_mov_b64_e32 v[54:55], 0
	v_mov_b64_e32 v[8:9], 0
	v_mov_b64_e32 v[10:11], 0
	v_mov_b64_e32 v[12:13], 0
	v_mov_b64_e32 v[14:15], 0
	v_mov_b64_e32 v[24:25], 0
	v_mov_b64_e32 v[26:27], 0
	v_mov_b64_e32 v[28:29], 0
	v_mov_b64_e32 v[30:31], 0
	v_mov_b64_e32 v[40:41], 0
	v_mov_b64_e32 v[42:43], 0
	v_mov_b64_e32 v[44:45], 0
	v_mov_b64_e32 v[46:47], 0
	v_mov_b64_e32 v[56:57], 0
	v_mov_b64_e32 v[58:59], 0
	v_mov_b64_e32 v[60:61], 0
	v_mov_b64_e32 v[62:63], 0
	v_mov_b64_e32 v[64:65], 0
	v_mov_b64_e32 v[66:67], 0
	v_mov_b64_e32 v[68:69], 0
	v_mov_b64_e32 v[70:71], 0
	v_mov_b64_e32 v[80:81], 0
	v_mov_b64_e32 v[82:83], 0
	v_mov_b64_e32 v[84:85], 0
	v_mov_b64_e32 v[86:87], 0
	v_mov_b64_e32 v[96:97], 0
	v_mov_b64_e32 v[98:99], 0
	v_mov_b64_e32 v[100:101], 0
	v_mov_b64_e32 v[102:103], 0
	v_mov_b64_e32 v[120:121], 0
	v_mov_b64_e32 v[122:123], 0
	v_mov_b64_e32 v[124:125], 0
	v_mov_b64_e32 v[126:127], 0
	v_mov_b64_e32 v[72:73], 0
	v_mov_b64_e32 v[74:75], 0
	v_mov_b64_e32 v[76:77], 0
	v_mov_b64_e32 v[78:79], 0
	v_mov_b64_e32 v[88:89], 0
	v_mov_b64_e32 v[90:91], 0
	v_mov_b64_e32 v[92:93], 0
	v_mov_b64_e32 v[94:95], 0
	v_mov_b64_e32 v[108:109], 0
	v_mov_b64_e32 v[110:111], 0
	v_mov_b64_e32 v[112:113], 0
	v_mov_b64_e32 v[114:115], 0
	v_mov_b64_e32 v[132:133], 0
	v_mov_b64_e32 v[134:135], 0
	v_mov_b64_e32 v[136:137], 0
	v_mov_b64_e32 v[138:139], 0

;     __device__ bool next(int i, Unit& u) const { const bool r = base.next(i >> 1, u); u.kh = i & 1; return r; }
; template <class Epi, class Sched, bool ALIGN_EPI = false, bool SP2 = false, bool ABLK = false, bool F8 = false>
; __device__ __forceinline__ void gemm_phase(PG8_LAS unsigned char* lds, const Gemm g, const Sched& S, const Epi& E, const int wave_s) {
;     ...
;         const bool has_next = S.next(ui + 1, nxt); nxt.par = (ui + 1) & 1;
;         const char* nA = has_next ? (const char*)g.A + (size_t)nxt.pm * tstep + nxt.kh * khbA : cA; const char* nB = has_next ? (const char*)g.Bt + (size_t)nxt.pn * tstep + nxt.kh * khb : cB;
;     ...
;         if (!(Epi::MID && cur.kh == 0))
; #pragma unroll
;         for (int a = 0; a < 2; ++a)
; #pragma unroll
;             for (int b = 0; b < 2; ++b)
; #pragma unroll
;                 for (int m = 0; m < 4; ++m)
; #pragma unroll
;                     for (int n = 0; n < 2; ++n) acc[a][b][m][n] = (f32x4){0.f, 0.f, 0.f, 0.f};
;         cur = nxt; cA = nA; cB = nB; ++ui;
.LBB0_394:
	s_ashr_i32 s53, s52, 31
	s_lshl_b64 s[54:55], s[52:53], 20
	s_add_u32 s54, s28, s54
	s_addc_u32 s55, s29, s55
	s_and_b64 s[56:57], s[10:11], exec
	s_cselect_b32 s20, s55, s63
	s_cselect_b32 s23, s54, s62
	s_ashr_i32 s51, s50, 31
	s_lshl_b64 s[56:57], s[50:51], 20
	s_add_u32 s56, s76, s56
	s_addc_u32 s57, s77, s57
	s_and_b64 s[66:67], s[10:11], exec
	s_cselect_b32 s51, s57, s65
	s_cselect_b32 s53, s56, s64
	s_add_u32 s62, s62, 0x80080
	s_addc_u32 s63, s63, 0
	s_add_u32 s59, s64, 0x100
	v_mov_b64_e32 v[0:1], 0
	s_addc_u32 s61, s65, 0
	s_mov_b32 vcc_lo, -2
	v_mov_b64_e32 v[2:3], 0
	v_mov_b64_e32 v[4:5], 0
	v_mov_b64_e32 v[6:7], 0
	v_mov_b64_e32 v[16:17], 0
	v_mov_b64_e32 v[18:19], 0
	v_mov_b64_e32 v[20:21], 0
	v_mov_b64_e32 v[22:23], 0
	v_mov_b64_e32 v[32:33], 0
	v_mov_b64_e32 v[34:35], 0
	v_mov_b64_e32 v[36:37], 0
	v_mov_b64_e32 v[38:39], 0
	v_mov_b64_e32 v[48:49], 0
	v_mov_b64_e32 v[50:51], 0
	v_mov_b64_e32 v[52:53], 0
	v_mov_b64_e32 v[54:55], 0
	v_mov_b64_e32 v[8:9], 0
	v_mov_b64_e32 v[10:11], 0
	v_mov_b64_e32 v[12:13], 0
	v_mov_b64_e32 v[14:15], 0
	v_mov_b64_e32 v[24:25], 0
	v_mov_b64_e32 v[26:27], 0
	v_mov_b64_e32 v[28:29], 0
	v_mov_b64_e32 v[30:31], 0
	v_mov_b64_e32 v[40:41], 0
	v_mov_b64_e32 v[42:43], 0
	v_mov_b64_e32 v[44:45], 0
	v_mov_b64_e32 v[46:47], 0
	v_mov_b64_e32 v[56:57], 0
	v_mov_b64_e32 v[58:59], 0
	v_mov_b64_e32 v[60:61], 0
	v_mov_b64_e32 v[62:63], 0
	v_mov_b64_e32 v[64:65], 0
	v_mov_b64_e32 v[66:67], 0
	v_mov_b64_e32 v[68:69], 0
	v_mov_b64_e32 v[70:71], 0
	v_mov_b64_e32 v[80:81], 0
	v_mov_b64_e32 v[82:83], 0
	v_mov_b64_e32 v[84:85], 0
	v_mov_b64_e32 v[86:87], 0
	v_mov_b64_e32 v[96:97], 0
	v_mov_b64_e32 v[98:99], 0
	v_mov_b64_e32 v[100:101], 0
	v_mov_b64_e32 v[102:103], 0
	v_mov_b64_e32 v[112:113], 0
	v_mov_b64_e32 v[114:115], 0
	v_mov_b64_e32 v[116:117], 0
	v_mov_b64_e32 v[118:119], 0
	v_mov_b64_e32 v[72:73], 0
	v_mov_b64_e32 v[74:75], 0
	v_mov_b64_e32 v[76:77], 0
	v_mov_b64_e32 v[78:79], 0
	v_mov_b64_e32 v[88:89], 0
	v_mov_b64_e32 v[90:91], 0
	v_mov_b64_e32 v[92:93], 0
	v_mov_b64_e32 v[94:95], 0
	v_mov_b64_e32 v[104:105], 0
	v_mov_b64_e32 v[106:107], 0
	v_mov_b64_e32 v[108:109], 0
	v_mov_b64_e32 v[110:111], 0
	v_mov_b64_e32 v[120:121], 0
	v_mov_b64_e32 v[122:123], 0
	v_mov_b64_e32 v[124:125], 0
	v_mov_b64_e32 v[126:127], 0

;     __device__ bool next(int i, Unit& u) const { const bool r = base.next(i >> 1, u); u.kh = i & 1; return r; }
; template <class Epi, class Sched, bool ALIGN_EPI = false, bool SP2 = false, bool ABLK = false, bool F8 = false>
; __device__ __forceinline__ void gemm_phase(PG8_LAS unsigned char* lds, const Gemm g, const Sched& S, const Epi& E, const int wave_s) {
;     ...
;         const bool has_next = S.next(ui + 1, nxt); nxt.par = (ui + 1) & 1;
;         const char* nA = has_next ? (const char*)g.A + (size_t)nxt.pm * tstep + nxt.kh * khbA : cA; const char* nB = has_next ? (const char*)g.Bt + (size_t)nxt.pn * tstep + nxt.kh * khb : cB;
;     ...
;         if (!(Epi::MID && cur.kh == 0))
; #pragma unroll
;         for (int a = 0; a < 2; ++a)
; #pragma unroll
;             for (int b = 0; b < 2; ++b)
; #pragma unroll
;                 for (int m = 0; m < 4; ++m)
; #pragma unroll
;                     for (int n = 0; n < 2; ++n) acc[a][b][m][n] = (f32x4){0.f, 0.f, 0.f, 0.f};
;         cur = nxt; cA = nA; cB = nB; ++ui;
.LBB0_591:
	s_ashr_i32 s51, s50, 31
	s_lshl_b64 s[52:53], s[50:51], 19
	s_add_u32 s52, s12, s52
	s_addc_u32 s53, s13, s53
	s_and_b64 s[54:55], s[10:11], exec
	s_cselect_b32 s51, s53, s61
	s_cselect_b32 s57, s52, s60
	s_ashr_i32 s49, s48, 31
	s_lshl_b64 s[54:55], s[48:49], 19
	s_add_u32 s54, s18, s54
	s_addc_u32 s55, s19, s55
	s_and_b64 s[64:65], s[10:11], exec
	s_cselect_b32 s49, s55, s63
	s_cselect_b32 s67, s54, s62
	s_add_u32 s60, s60, 0x40080
	s_addc_u32 s61, s61, 0
	s_add_u32 s74, s62, 0x100
	v_mov_b64_e32 v[0:1], 0
	s_addc_u32 s75, s63, 0
	s_mov_b32 s76, -2
	s_waitcnt lgkmcnt(0)
	v_mov_b64_e32 v[2:3], 0
	v_mov_b64_e32 v[4:5], 0
	v_mov_b64_e32 v[6:7], 0
	s_waitcnt vmcnt(0)
	v_mov_b64_e32 v[16:17], 0
	v_mov_b64_e32 v[18:19], 0
	v_mov_b64_e32 v[20:21], 0
	v_mov_b64_e32 v[22:23], 0
	v_mov_b64_e32 v[32:33], 0
	v_mov_b64_e32 v[34:35], 0
	v_mov_b64_e32 v[36:37], 0
	v_mov_b64_e32 v[38:39], 0
	v_mov_b64_e32 v[48:49], 0
	v_mov_b64_e32 v[50:51], 0
	v_mov_b64_e32 v[52:53], 0
	v_mov_b64_e32 v[54:55], 0
	v_mov_b64_e32 v[8:9], 0
	v_mov_b64_e32 v[10:11], 0
	v_mov_b64_e32 v[12:13], 0
	v_mov_b64_e32 v[14:15], 0
	v_mov_b64_e32 v[24:25], 0
	v_mov_b64_e32 v[26:27], 0
	v_mov_b64_e32 v[28:29], 0
	v_mov_b64_e32 v[30:31], 0
	v_mov_b64_e32 v[40:41], 0
	v_mov_b64_e32 v[42:43], 0
	v_mov_b64_e32 v[44:45], 0
	v_mov_b64_e32 v[46:47], 0
	v_mov_b64_e32 v[56:57], 0
	v_mov_b64_e32 v[58:59], 0
	v_mov_b64_e32 v[60:61], 0
	v_mov_b64_e32 v[62:63], 0
	v_mov_b64_e32 v[72:73], 0
	v_mov_b64_e32 v[74:75], 0
	v_mov_b64_e32 v[84:85], 0
	v_mov_b64_e32 v[86:87], 0
	v_mov_b64_e32 v[104:105], 0
	v_mov_b64_e32 v[106:107], 0
	v_mov_b64_e32 v[108:109], 0
	v_mov_b64_e32 v[110:111], 0
	v_mov_b64_e32 v[128:129], 0
	v_mov_b64_e32 v[130:131], 0
	v_mov_b64_e32 v[132:133], 0
	v_mov_b64_e32 v[134:135], 0
	v_mov_b64_e32 v[152:153], 0
	v_mov_b64_e32 v[154:155], 0
	v_mov_b64_e32 v[156:157], 0
	v_mov_b64_e32 v[158:159], 0
	v_mov_b64_e32 v[92:93], 0
	v_mov_b64_e32 v[94:95], 0
	v_mov_b64_e32 v[96:97], 0
	v_mov_b64_e32 v[98:99], 0
	v_mov_b64_e32 v[116:117], 0
	v_mov_b64_e32 v[118:119], 0
	v_mov_b64_e32 v[120:121], 0
	v_mov_b64_e32 v[122:123], 0
	v_mov_b64_e32 v[140:141], 0
	v_mov_b64_e32 v[142:143], 0
	v_mov_b64_e32 v[148:149], 0
	v_mov_b64_e32 v[150:151], 0
	v_mov_b64_e32 v[168:169], 0
	v_mov_b64_e32 v[170:171], 0
	v_mov_b64_e32 v[172:173], 0
	v_mov_b64_e32 v[174:175], 0

;     __device__ bool next(int i, Unit& u) const { const bool r = base.next(i >> 1, u); u.kh = i & 1; return r; }
; template <class Epi, class Sched, bool ALIGN_EPI = false, bool SP2 = false, bool ABLK = false, bool F8 = false>
; __device__ __forceinline__ void gemm_phase(PG8_LAS unsigned char* lds, const Gemm g, const Sched& S, const Epi& E, const int wave_s) {
;     ...
;         const bool has_next = S.next(ui + 1, nxt); nxt.par = (ui + 1) & 1;
;         const char* nA = has_next ? (const char*)g.A + (size_t)nxt.pm * tstep + nxt.kh * khbA : cA; const char* nB = has_next ? (const char*)g.Bt + (size_t)nxt.pn * tstep + nxt.kh * khb : cB;
;     ...
;         if (!(Epi::MID && cur.kh == 0))
; #pragma unroll
;         for (int a = 0; a < 2; ++a)
; #pragma unroll
;             for (int b = 0; b < 2; ++b)
; #pragma unroll
;                 for (int m = 0; m < 4; ++m)
; #pragma unroll
;                     for (int n = 0; n < 2; ++n) acc[a][b][m][n] = (f32x4){0.f, 0.f, 0.f, 0.f};
;         cur = nxt; cA = nA; cB = nB; ++ui;
.LBB0_809:
	s_ashr_i32 s43, s42, 31
	s_and_b32 s64, s63, 1
	s_lshl_b64 s[46:47], s[42:43], 19
	s_add_u32 s46, s38, s46
	s_addc_u32 s47, s39, s47
	s_and_b64 s[48:49], exec, s[10:11]
	s_cselect_b32 s43, s55, s47
	s_cselect_b32 s66, s54, s46
	s_ashr_i32 s41, s40, 31
	s_lshl_b64 s[48:49], s[40:41], 19
	s_add_u32 s48, s18, s48
	s_addc_u32 s49, s19, s49
	s_and_b64 s[58:59], exec, s[10:11]
	s_cselect_b32 s41, s57, s49
	s_cselect_b32 s67, s56, s48
	s_lshl_b32 s58, s42, 8
	s_ashr_i32 s59, s58, 31
	s_lshl_b32 s75, s64, 10
	s_or_b64 s[10:11], s[44:45], s[10:11]
	s_add_u32 s54, s54, 0x40080
	s_addc_u32 s55, s55, 0
	s_add_u32 s72, s56, 0x100
	v_mov_b64_e32 v[0:1], 0
	v_lshl_add_u64 v[228:229], s[58:59], 2, v[130:131]
	s_addc_u32 s73, s57, 0
	s_mov_b32 s74, -2
	s_add_i32 s75, s95, s75
	v_mov_b64_e32 v[2:3], 0
	v_mov_b64_e32 v[8:9], 0
	v_mov_b64_e32 v[10:11], 0
	v_mov_b64_e32 v[16:17], 0
	v_mov_b64_e32 v[18:19], 0
	v_mov_b64_e32 v[24:25], 0
	v_mov_b64_e32 v[26:27], 0
	v_mov_b64_e32 v[32:33], 0
	v_mov_b64_e32 v[34:35], 0
	v_mov_b64_e32 v[40:41], 0
	v_mov_b64_e32 v[42:43], 0
	v_mov_b64_e32 v[48:49], 0
	v_mov_b64_e32 v[50:51], 0
	v_mov_b64_e32 v[56:57], 0
	v_mov_b64_e32 v[58:59], 0
	v_mov_b64_e32 v[4:5], 0
	v_mov_b64_e32 v[6:7], 0
	v_mov_b64_e32 v[12:13], 0
	v_mov_b64_e32 v[14:15], 0
	v_mov_b64_e32 v[20:21], 0
	v_mov_b64_e32 v[22:23], 0
	v_mov_b64_e32 v[28:29], 0
	v_mov_b64_e32 v[30:31], 0
	v_mov_b64_e32 v[36:37], 0
	v_mov_b64_e32 v[38:39], 0
	v_mov_b64_e32 v[44:45], 0
	v_mov_b64_e32 v[46:47], 0
	v_mov_b64_e32 v[52:53], 0
	v_mov_b64_e32 v[54:55], 0
	v_mov_b64_e32 v[60:61], 0
	v_mov_b64_e32 v[62:63], 0
	v_mov_b64_e32 v[64:65], 0
	v_mov_b64_e32 v[66:67], 0
	v_mov_b64_e32 v[72:73], 0
	v_mov_b64_e32 v[74:75], 0
	v_mov_b64_e32 v[80:81], 0
	v_mov_b64_e32 v[82:83], 0
	v_mov_b64_e32 v[88:89], 0
	v_mov_b64_e32 v[90:91], 0
	v_mov_b64_e32 v[96:97], 0
	v_mov_b64_e32 v[98:99], 0
	v_mov_b64_e32 v[104:105], 0
	v_mov_b64_e32 v[106:107], 0
	v_mov_b64_e32 v[112:113], 0
	v_mov_b64_e32 v[114:115], 0
	v_mov_b64_e32 v[120:121], 0
	v_mov_b64_e32 v[122:123], 0
	v_mov_b64_e32 v[68:69], 0
	v_mov_b64_e32 v[70:71], 0
	v_mov_b64_e32 v[76:77], 0
	v_mov_b64_e32 v[78:79], 0
	v_mov_b64_e32 v[84:85], 0
	v_mov_b64_e32 v[86:87], 0
	v_mov_b64_e32 v[92:93], 0
	v_mov_b64_e32 v[94:95], 0
	v_mov_b64_e32 v[100:101], 0
	v_mov_b64_e32 v[102:103], 0
	v_mov_b64_e32 v[108:109], 0
	v_mov_b64_e32 v[110:111], 0
	v_mov_b64_e32 v[116:117], 0
	v_mov_b64_e32 v[118:119], 0
	v_mov_b64_e32 v[124:125], 0
	v_mov_b64_e32 v[126:127], 0
	s_branch .LBB0_811

; template <class Epi, class Sched, bool ALIGN_EPI = false, bool SP2 = false, bool ABLK = false, bool F8 = false>
; __device__ __forceinline__ void gemm_phase(PG8_LAS unsigned char* lds, const Gemm g, const Sched& S, const Epi& E, const int wave_s) {
;     ...
;         if (!(Epi::MID && cur.kh == 0))
; #pragma unroll
;         for (int a = 0; a < 2; ++a)
; #pragma unroll
;             for (int b = 0; b < 2; ++b)
; #pragma unroll
;                 for (int m = 0; m < 4; ++m)
; #pragma unroll
;                     for (int n = 0; n < 2; ++n) acc[a][b][m][n] = (f32x4){0.f, 0.f, 0.f, 0.f};
;         cur = nxt; cA = nA; cB = nB; ++ui;
.LBB0_893:
	s_add_u32 s60, s44, 0x100
	s_addc_u32 s61, s45, 0
	s_add_u32 s44, s46, 0xc000
	v_mov_b64_e32 v[0:1], 0
	s_addc_u32 s45, s47, 0
	s_mov_b32 s62, -2
	s_waitcnt lgkmcnt(0)
	v_mov_b64_e32 v[2:3], 0
	v_mov_b64_e32 v[4:5], 0
	v_mov_b64_e32 v[6:7], 0
	v_mov_b64_e32 v[16:17], 0
	v_mov_b64_e32 v[18:19], 0
	v_mov_b64_e32 v[20:21], 0
	v_mov_b64_e32 v[22:23], 0
	v_mov_b64_e32 v[32:33], 0
	v_mov_b64_e32 v[34:35], 0
	v_mov_b64_e32 v[36:37], 0
	v_mov_b64_e32 v[38:39], 0
	v_mov_b64_e32 v[48:49], 0
	v_mov_b64_e32 v[50:51], 0
	v_mov_b64_e32 v[52:53], 0
	v_mov_b64_e32 v[54:55], 0
	v_mov_b64_e32 v[8:9], 0
	v_mov_b64_e32 v[10:11], 0
	v_mov_b64_e32 v[12:13], 0
	v_mov_b64_e32 v[14:15], 0
	v_mov_b64_e32 v[24:25], 0
	v_mov_b64_e32 v[26:27], 0
	v_mov_b64_e32 v[28:29], 0
	v_mov_b64_e32 v[30:31], 0
	v_mov_b64_e32 v[40:41], 0
	v_mov_b64_e32 v[42:43], 0
	v_mov_b64_e32 v[44:45], 0
	v_mov_b64_e32 v[46:47], 0
	v_mov_b64_e32 v[56:57], 0
	v_mov_b64_e32 v[58:59], 0
	v_mov_b64_e32 v[60:61], 0
	v_mov_b64_e32 v[62:63], 0
	v_mov_b64_e32 v[64:65], 0
	v_mov_b64_e32 v[66:67], 0
	v_mov_b64_e32 v[68:69], 0
	v_mov_b64_e32 v[70:71], 0
	v_mov_b64_e32 v[80:81], 0
	v_mov_b64_e32 v[82:83], 0
	v_mov_b64_e32 v[84:85], 0
	v_mov_b64_e32 v[86:87], 0
	v_mov_b64_e32 v[96:97], 0
	v_mov_b64_e32 v[98:99], 0
	v_mov_b64_e32 v[100:101], 0
	v_mov_b64_e32 v[102:103], 0
	v_mov_b64_e32 v[120:121], 0
	v_mov_b64_e32 v[122:123], 0
	v_mov_b64_e32 v[124:125], 0
	v_mov_b64_e32 v[126:127], 0
	v_mov_b64_e32 v[72:73], 0
	v_mov_b64_e32 v[74:75], 0
	v_mov_b64_e32 v[76:77], 0
	v_mov_b64_e32 v[78:79], 0
	v_mov_b64_e32 v[88:89], 0
	v_mov_b64_e32 v[90:91], 0
	v_mov_b64_e32 v[92:93], 0
	v_mov_b64_e32 v[94:95], 0
	v_mov_b64_e32 v[108:109], 0
	v_mov_b64_e32 v[110:111], 0
	v_mov_b64_e32 v[112:113], 0
	v_mov_b64_e32 v[114:115], 0
	v_mov_b64_e32 v[132:133], 0
	v_mov_b64_e32 v[134:135], 0
	v_mov_b64_e32 v[136:137], 0
	v_mov_b64_e32 v[138:139], 0

;     __device__ bool next(int i, Unit& u) const { const bool r = base.next(i >> 1, u); u.kh = i & 1; return r; }
; template <class Epi, class Sched, bool ALIGN_EPI = false, bool SP2 = false, bool ABLK = false, bool F8 = false>
; __device__ __forceinline__ void gemm_phase(PG8_LAS unsigned char* lds, const Gemm g, const Sched& S, const Epi& E, const int wave_s) {
;     ...
;         const bool has_next = S.next(ui + 1, nxt); nxt.par = (ui + 1) & 1;
;         const char* nA = has_next ? (const char*)g.A + (size_t)nxt.pm * tstep + nxt.kh * khbA : cA; const char* nB = has_next ? (const char*)g.Bt + (size_t)nxt.pn * tstep + nxt.kh * khb : cB;
;     ...
;         if (!(Epi::MID && cur.kh == 0))
; #pragma unroll
;         for (int a = 0; a < 2; ++a)
; #pragma unroll
;             for (int b = 0; b < 2; ++b)
; #pragma unroll
;                 for (int m = 0; m < 4; ++m)
; #pragma unroll
;                     for (int n = 0; n < 2; ++n) acc[a][b][m][n] = (f32x4){0.f, 0.f, 0.f, 0.f};
;         cur = nxt; cA = nA; cB = nB; ++ui;
.LBB0_1009:
	s_ashr_i32 s41, s40, 31
	s_lshl_b64 s[42:43], s[40:41], 20
	s_add_u32 s42, s28, s42
	s_addc_u32 s43, s29, s43
	s_and_b64 s[44:45], s[6:7], exec
	s_cselect_b32 s41, s43, s51
	s_cselect_b32 s47, s42, s50
	s_ashr_i32 s13, s12, 31
	s_lshl_b64 s[44:45], s[12:13], 20
	s_add_u32 s44, s18, s44
	s_addc_u32 s45, s19, s45
	s_and_b64 s[54:55], s[6:7], exec
	s_cselect_b32 s13, s45, s53
	s_cselect_b32 s59, s44, s52
	s_add_u32 s50, s50, 0x80080
	s_addc_u32 s51, s51, 0
	s_add_u32 s60, s52, 0x100
	v_mov_b64_e32 v[0:1], 0
	s_addc_u32 s61, s53, 0
	s_mov_b32 s62, -2
	s_waitcnt lgkmcnt(0)
	v_mov_b64_e32 v[2:3], 0
	v_mov_b64_e32 v[4:5], 0
	v_mov_b64_e32 v[6:7], 0
	v_mov_b64_e32 v[16:17], 0
	v_mov_b64_e32 v[18:19], 0
	v_mov_b64_e32 v[20:21], 0
	v_mov_b64_e32 v[22:23], 0
	v_mov_b64_e32 v[32:33], 0
	v_mov_b64_e32 v[34:35], 0
	v_mov_b64_e32 v[36:37], 0
	v_mov_b64_e32 v[38:39], 0
	v_mov_b64_e32 v[48:49], 0
	v_mov_b64_e32 v[50:51], 0
	v_mov_b64_e32 v[52:53], 0
	v_mov_b64_e32 v[54:55], 0
	v_mov_b64_e32 v[8:9], 0
	v_mov_b64_e32 v[10:11], 0
	v_mov_b64_e32 v[12:13], 0
	v_mov_b64_e32 v[14:15], 0
	v_mov_b64_e32 v[24:25], 0
	v_mov_b64_e32 v[26:27], 0
	v_mov_b64_e32 v[28:29], 0
	v_mov_b64_e32 v[30:31], 0
	v_mov_b64_e32 v[40:41], 0
	v_mov_b64_e32 v[42:43], 0
	v_mov_b64_e32 v[44:45], 0
	v_mov_b64_e32 v[46:47], 0
	v_mov_b64_e32 v[56:57], 0
	v_mov_b64_e32 v[58:59], 0
	v_mov_b64_e32 v[60:61], 0
	v_mov_b64_e32 v[62:63], 0
	v_mov_b64_e32 v[72:73], 0
	v_mov_b64_e32 v[74:75], 0
	v_mov_b64_e32 v[76:77], 0
	v_mov_b64_e32 v[78:79], 0
	v_mov_b64_e32 v[96:97], 0
	v_mov_b64_e32 v[98:99], 0
	v_mov_b64_e32 v[100:101], 0
	v_mov_b64_e32 v[102:103], 0
	v_mov_b64_e32 v[120:121], 0
	v_mov_b64_e32 v[122:123], 0
	v_mov_b64_e32 v[124:125], 0
	v_mov_b64_e32 v[126:127], 0
	v_mov_b64_e32 v[144:145], 0
	v_mov_b64_e32 v[146:147], 0
	v_mov_b64_e32 v[148:149], 0
	v_mov_b64_e32 v[150:151], 0
	v_mov_b64_e32 v[80:81], 0
	v_mov_b64_e32 v[82:83], 0
	v_mov_b64_e32 v[84:85], 0
	v_mov_b64_e32 v[86:87], 0
	v_mov_b64_e32 v[104:105], 0
	v_mov_b64_e32 v[106:107], 0
	v_mov_b64_e32 v[108:109], 0
	v_mov_b64_e32 v[110:111], 0
	v_mov_b64_e32 v[128:129], 0
	v_mov_b64_e32 v[130:131], 0
	v_mov_b64_e32 v[132:133], 0
	v_mov_b64_e32 v[134:135], 0
	v_mov_b64_e32 v[156:157], 0
	v_mov_b64_e32 v[158:159], 0
	v_mov_b64_e32 v[160:161], 0
	v_mov_b64_e32 v[162:163], 0
